# EpiQ rstd ladder (both layers): next row group's 4 partial-sum loads issued as soon as the current group's values are consumed (16-register dead buffer, constant offsets from the group-0 base)
# baseline (speedup 1.0000x reference)
.LBB0_573:
	v_mov_b32_e32 v34, v0
	s_lshl_b32 s4, s6, 8
	s_add_i32 s4, s4, s91
	v_and_b32_e32 v139, 15, v34
	v_or_b32_e32 v140, s4, v139
	v_ashrrev_i32_e32 v141, 31, v140
	v_lshlrev_b64 v[142:143], 6, v[140:141]
	v_lshl_add_u64 v[154:155], s[30:31], 0, v[142:143]
	s_mov_b32 s100, 0x2000
	s_mov_b32 s101, 0
	v_mov_b64_e32 v[232:233], v[154:155]
	v_lshl_add_u64 v[234:235], v[154:155], 0, s[100:101]
	global_load_dwordx4 v[216:219], v[232:233], off offset:32
	global_load_dwordx4 v[220:223], v[232:233], off offset:48
	global_load_dwordx4 v[224:227], v[232:233], off
	global_load_dwordx4 v[228:231], v[232:233], off offset:16
	v_bfe_u32 v199, v34, 4, 2
	s_lshl_b32 s2, s2, 8
	s_waitcnt vmcnt(0)
	v_pk_add_f32 v[144:145], v[218:219], v[222:223]
	v_pk_add_f32 v[142:143], v[216:217], v[220:221]
	v_pk_add_f32 v[152:153], v[226:227], v[230:231]
	v_pk_add_f32 v[150:151], v[224:225], v[228:229]
	global_load_dwordx4 v[216:219], v[232:233], off offset:1056
	global_load_dwordx4 v[220:223], v[232:233], off offset:1072
	global_load_dwordx4 v[224:227], v[232:233], off offset:1024
	global_load_dwordx4 v[228:231], v[232:233], off offset:1040
	v_pk_add_f32 v[144:145], v[152:153], v[144:145]
	v_pk_add_f32 v[142:143], v[150:151], v[142:143]
	s_nop 0
	v_add_f32_e32 v34, v142, v143
	v_add_f32_e32 v142, v144, v145
	v_add_f32_e32 v34, v34, v142
	v_fmamk_f32 v34, v34, 0x3b000000, v169
	v_cmp_gt_f32_e32 vcc, s96, v34
	v_mul_f32_e32 v142, 0x4f800000, v34
	s_nop 0
	v_cndmask_b32_e32 v34, v34, v142, vcc
	v_sqrt_f32_e32 v142, v34
	s_nop 0
	v_add_u32_e32 v143, -1, v142
	v_fma_f32 v144, -v143, v142, v34
	v_cmp_ge_f32_e64 s[6:7], 0, v144
	v_add_u32_e32 v144, 1, v142
	s_nop 0
	v_cndmask_b32_e64 v143, v142, v143, s[6:7]
	v_fma_f32 v142, -v144, v142, v34
	v_cmp_lt_f32_e64 s[6:7], 0, v142
	s_nop 1
	v_cndmask_b32_e64 v142, v143, v144, s[6:7]
	v_mul_f32_e32 v143, 0x37800000, v142
	v_cndmask_b32_e32 v142, v142, v143, vcc
	v_cmp_class_f32_e32 vcc, v34, v173
	s_nop 1
	v_cndmask_b32_e32 v34, v142, v34, vcc
	v_div_scale_f32 v142, s[6:7], v34, v34, 1.0
	v_rcp_f32_e32 v143, v142
	s_nop 0
	v_fma_f32 v144, -v142, v143, 1.0
	v_fmac_f32_e32 v143, v144, v143
	v_div_scale_f32 v144, vcc, 1.0, v34, 1.0
	v_mul_f32_e32 v145, v144, v143
	v_fma_f32 v146, -v142, v145, v144
	v_fmac_f32_e32 v145, v146, v143
	v_fma_f32 v142, -v142, v145, v144
	v_div_fmas_f32 v142, v142, v143, v145
	v_div_fixup_f32 v202, v142, v34, 1.0
	v_or_b32_e32 v142, 16, v140
	v_ashrrev_i32_e32 v143, 31, v142
	v_lshlrev_b64 v[144:145], 6, v[142:143]
	v_lshl_add_u64 v[158:159], s[30:31], 0, v[144:145]
	v_mul_f32_e32 v184, 0x3f553b94, v202
	v_lshlrev_b64 v[182:183], 7, v[142:143]
	s_waitcnt vmcnt(2)
	v_pk_add_f32 v[146:147], v[218:219], v[222:223]
	v_pk_add_f32 v[144:145], v[216:217], v[220:221]
	s_waitcnt vmcnt(0)
	v_pk_add_f32 v[154:155], v[226:227], v[230:231]
	v_pk_add_f32 v[152:153], v[224:225], v[228:229]
	global_load_dwordx4 v[216:219], v[232:233], off offset:2080
	global_load_dwordx4 v[220:223], v[232:233], off offset:2096
	global_load_dwordx4 v[224:227], v[232:233], off offset:2048
	global_load_dwordx4 v[228:231], v[232:233], off offset:2064
	v_pk_add_f32 v[146:147], v[154:155], v[146:147]
	v_pk_add_f32 v[144:145], v[152:153], v[144:145]
	s_nop 0
	v_add_f32_e32 v34, v144, v145
	v_add_f32_e32 v144, v146, v147
	v_add_f32_e32 v34, v34, v144
	v_fmamk_f32 v34, v34, 0x3b000000, v169
	v_cmp_gt_f32_e32 vcc, s96, v34
	v_mul_f32_e32 v144, 0x4f800000, v34
	s_nop 0
	v_cndmask_b32_e32 v34, v34, v144, vcc
	v_sqrt_f32_e32 v144, v34
	s_nop 0
	v_add_u32_e32 v145, -1, v144
	v_fma_f32 v146, -v145, v144, v34
	v_cmp_ge_f32_e64 s[6:7], 0, v146
	v_add_u32_e32 v146, 1, v144
	s_nop 0
	v_cndmask_b32_e64 v145, v144, v145, s[6:7]
	v_fma_f32 v144, -v146, v144, v34
	v_cmp_lt_f32_e64 s[6:7], 0, v144
	s_nop 1
	v_cndmask_b32_e64 v144, v145, v146, s[6:7]
	v_mul_f32_e32 v145, 0x37800000, v144
	v_cndmask_b32_e32 v144, v144, v145, vcc
	v_cmp_class_f32_e32 vcc, v34, v173
	s_nop 1
	v_cndmask_b32_e32 v34, v144, v34, vcc
	v_div_scale_f32 v144, s[6:7], v34, v34, 1.0
	v_rcp_f32_e32 v145, v144
	s_nop 0
	v_fma_f32 v146, -v144, v145, 1.0
	v_fmac_f32_e32 v145, v146, v145
	v_div_scale_f32 v146, vcc, 1.0, v34, 1.0
	v_mul_f32_e32 v147, v146, v145
	v_fma_f32 v148, -v144, v147, v146
	v_fmac_f32_e32 v147, v148, v145
	v_fma_f32 v144, -v144, v147, v146
	v_div_fmas_f32 v144, v144, v145, v147
	v_div_fixup_f32 v203, v144, v34, 1.0
	v_or_b32_e32 v144, 32, v140
	v_ashrrev_i32_e32 v145, 31, v144
	v_lshlrev_b64 v[146:147], 6, v[144:145]
	v_lshl_add_u64 v[154:155], s[30:31], 0, v[146:147]
	v_mul_f32_e32 v180, 0x3f553b94, v203
	v_lshlrev_b64 v[178:179], 7, v[144:145]
	s_waitcnt vmcnt(2)
	v_pk_add_f32 v[148:149], v[218:219], v[222:223]
	v_pk_add_f32 v[146:147], v[216:217], v[220:221]
	s_waitcnt vmcnt(0)
	v_pk_add_f32 v[154:155], v[226:227], v[230:231]
	v_pk_add_f32 v[158:159], v[224:225], v[228:229]
	global_load_dwordx4 v[216:219], v[232:233], off offset:3104
	global_load_dwordx4 v[220:223], v[232:233], off offset:3120
	global_load_dwordx4 v[224:227], v[232:233], off offset:3072
	global_load_dwordx4 v[228:231], v[232:233], off offset:3088
	v_pk_add_f32 v[148:149], v[154:155], v[148:149]
	v_pk_add_f32 v[146:147], v[158:159], v[146:147]
	s_nop 0
	v_add_f32_e32 v34, v146, v147
	v_add_f32_e32 v146, v148, v149
	v_add_f32_e32 v34, v34, v146
	v_fmamk_f32 v34, v34, 0x3b000000, v169
	v_cmp_gt_f32_e32 vcc, s96, v34
	v_mul_f32_e32 v146, 0x4f800000, v34
	s_nop 0
	v_cndmask_b32_e32 v34, v34, v146, vcc
	v_sqrt_f32_e32 v146, v34
	s_nop 0
	v_add_u32_e32 v147, -1, v146
	v_fma_f32 v148, -v147, v146, v34
	v_cmp_ge_f32_e64 s[6:7], 0, v148
	v_add_u32_e32 v148, 1, v146
	s_nop 0
	v_cndmask_b32_e64 v147, v146, v147, s[6:7]
	v_fma_f32 v146, -v148, v146, v34
	v_cmp_lt_f32_e64 s[6:7], 0, v146
	s_nop 1
	v_cndmask_b32_e64 v146, v147, v148, s[6:7]
	v_mul_f32_e32 v147, 0x37800000, v146
	v_cndmask_b32_e32 v146, v146, v147, vcc
	v_cmp_class_f32_e32 vcc, v34, v173
	s_nop 1
	v_cndmask_b32_e32 v34, v146, v34, vcc
	v_div_scale_f32 v146, s[6:7], v34, v34, 1.0
	v_rcp_f32_e32 v147, v146
	s_nop 0
	v_fma_f32 v148, -v146, v147, 1.0
	v_fmac_f32_e32 v147, v148, v147
	v_div_scale_f32 v148, vcc, 1.0, v34, 1.0
	v_mul_f32_e32 v149, v148, v147
	v_fma_f32 v150, -v146, v149, v148
	v_fmac_f32_e32 v149, v150, v147
	v_fma_f32 v146, -v146, v149, v148
	v_div_fmas_f32 v146, v146, v147, v149
	v_div_fixup_f32 v205, v146, v34, 1.0
	v_or_b32_e32 v146, 48, v140
	v_ashrrev_i32_e32 v147, 31, v146
	v_lshlrev_b64 v[148:149], 6, v[146:147]
	v_lshl_add_u64 v[158:159], s[30:31], 0, v[148:149]
	v_mul_f32_e32 v176, 0x3f553b94, v205
	v_lshlrev_b64 v[174:175], 7, v[146:147]
	s_waitcnt vmcnt(2)
	v_pk_add_f32 v[150:151], v[218:219], v[222:223]
	v_pk_add_f32 v[148:149], v[216:217], v[220:221]
	s_waitcnt vmcnt(0)
	v_pk_add_f32 v[158:159], v[226:227], v[230:231]
	v_pk_add_f32 v[162:163], v[224:225], v[228:229]
	global_load_dwordx4 v[216:219], v[234:235], off offset:32
	global_load_dwordx4 v[220:223], v[234:235], off offset:48
	global_load_dwordx4 v[224:227], v[234:235], off
	global_load_dwordx4 v[228:231], v[234:235], off offset:16
	v_pk_add_f32 v[150:151], v[158:159], v[150:151]
	v_pk_add_f32 v[148:149], v[162:163], v[148:149]
	s_nop 0
	v_add_f32_e32 v34, v148, v149
	v_add_f32_e32 v148, v150, v151
	v_add_f32_e32 v34, v34, v148
	v_fmamk_f32 v34, v34, 0x3b000000, v169
	v_cmp_gt_f32_e32 vcc, s96, v34
	v_mul_f32_e32 v148, 0x4f800000, v34
	s_nop 0
	v_cndmask_b32_e32 v34, v34, v148, vcc
	v_sqrt_f32_e32 v148, v34
	s_nop 0
	v_add_u32_e32 v149, -1, v148
	v_fma_f32 v150, -v149, v148, v34
	v_cmp_ge_f32_e64 s[6:7], 0, v150
	v_add_u32_e32 v150, 1, v148
	s_nop 0
	v_cndmask_b32_e64 v149, v148, v149, s[6:7]
	v_fma_f32 v148, -v150, v148, v34
	v_cmp_lt_f32_e64 s[6:7], 0, v148
	s_nop 1
	v_cndmask_b32_e64 v148, v149, v150, s[6:7]
	v_mul_f32_e32 v149, 0x37800000, v148
	v_cndmask_b32_e32 v148, v148, v149, vcc
	v_cmp_class_f32_e32 vcc, v34, v173
	s_nop 1
	v_cndmask_b32_e32 v34, v148, v34, vcc
	v_div_scale_f32 v148, s[6:7], v34, v34, 1.0
	v_rcp_f32_e32 v149, v148
	s_nop 0
	v_fma_f32 v150, -v148, v149, 1.0
	v_fmac_f32_e32 v149, v150, v149
	v_div_scale_f32 v150, vcc, 1.0, v34, 1.0
	v_mul_f32_e32 v151, v150, v149
	v_fma_f32 v152, -v148, v151, v150
	v_fmac_f32_e32 v151, v152, v149
	v_fma_f32 v148, -v148, v151, v150
	v_div_fmas_f32 v148, v148, v149, v151
	v_div_fixup_f32 v206, v148, v34, 1.0
	v_add_u32_e32 v148, 0x80, v140
	v_ashrrev_i32_e32 v149, 31, v148
	v_lshlrev_b64 v[150:151], 6, v[148:149]
	v_lshl_add_u64 v[154:155], s[30:31], 0, v[150:151]
	v_mul_f32_e32 v172, 0x3f553b94, v206
	s_waitcnt vmcnt(2)
	v_pk_add_f32 v[152:153], v[218:219], v[222:223]
	v_pk_add_f32 v[150:151], v[216:217], v[220:221]
	s_waitcnt vmcnt(0)
	v_pk_add_f32 v[154:155], v[226:227], v[230:231]
	v_pk_add_f32 v[158:159], v[224:225], v[228:229]
	global_load_dwordx4 v[216:219], v[234:235], off offset:1056
	global_load_dwordx4 v[220:223], v[234:235], off offset:1072
	global_load_dwordx4 v[224:227], v[234:235], off offset:1024
	global_load_dwordx4 v[228:231], v[234:235], off offset:1040
	v_pk_add_f32 v[152:153], v[154:155], v[152:153]
	v_pk_add_f32 v[150:151], v[158:159], v[150:151]
	s_nop 0
	v_add_f32_e32 v34, v150, v151
	v_add_f32_e32 v150, v152, v153
	v_add_f32_e32 v34, v34, v150
	v_fmamk_f32 v34, v34, 0x3b000000, v169
	v_cmp_gt_f32_e32 vcc, s96, v34
	v_mul_f32_e32 v150, 0x4f800000, v34
	s_nop 0
	v_cndmask_b32_e32 v34, v34, v150, vcc
	v_sqrt_f32_e32 v150, v34
	s_nop 0
	v_add_u32_e32 v151, -1, v150
	v_fma_f32 v152, -v151, v150, v34
	v_cmp_ge_f32_e64 s[6:7], 0, v152
	v_add_u32_e32 v152, 1, v150
	s_nop 0
	v_cndmask_b32_e64 v151, v150, v151, s[6:7]
	v_fma_f32 v150, -v152, v150, v34
	v_cmp_lt_f32_e64 s[6:7], 0, v150
	s_nop 1
	v_cndmask_b32_e64 v150, v151, v152, s[6:7]
	v_mul_f32_e32 v151, 0x37800000, v150
	v_cndmask_b32_e32 v150, v150, v151, vcc
	v_cmp_class_f32_e32 vcc, v34, v173
	s_nop 1
	v_cndmask_b32_e32 v34, v150, v34, vcc
	v_div_scale_f32 v150, s[6:7], v34, v34, 1.0
	v_rcp_f32_e32 v151, v150
	s_nop 0
	v_fma_f32 v152, -v150, v151, 1.0
	v_fmac_f32_e32 v151, v152, v151
	v_div_scale_f32 v152, vcc, 1.0, v34, 1.0
	v_mul_f32_e32 v153, v152, v151
	v_fma_f32 v154, -v150, v153, v152
	v_fmac_f32_e32 v153, v154, v151
	v_fma_f32 v150, -v150, v153, v152
	v_div_fmas_f32 v150, v150, v151, v153
	v_div_fixup_f32 v200, v150, v34, 1.0
	v_add_u32_e32 v150, 0x90, v140
	v_ashrrev_i32_e32 v151, 31, v150
	v_lshlrev_b64 v[152:153], 6, v[150:151]
	v_lshl_add_u64 v[158:159], s[30:31], 0, v[152:153]
	v_mul_f32_e32 v168, 0x3f553b94, v200
	s_waitcnt vmcnt(2)
	v_pk_add_f32 v[154:155], v[218:219], v[222:223]
	v_pk_add_f32 v[152:153], v[216:217], v[220:221]
	s_waitcnt vmcnt(0)
	v_pk_add_f32 v[158:159], v[226:227], v[230:231]
	v_pk_add_f32 v[162:163], v[224:225], v[228:229]
	global_load_dwordx4 v[216:219], v[234:235], off offset:2080
	global_load_dwordx4 v[220:223], v[234:235], off offset:2096
	global_load_dwordx4 v[224:227], v[234:235], off offset:2048
	global_load_dwordx4 v[228:231], v[234:235], off offset:2064
	v_pk_add_f32 v[154:155], v[158:159], v[154:155]
	v_pk_add_f32 v[152:153], v[162:163], v[152:153]
	s_nop 0
	v_add_f32_e32 v34, v152, v153
	v_add_f32_e32 v152, v154, v155
	v_add_f32_e32 v34, v34, v152
	v_fmamk_f32 v34, v34, 0x3b000000, v169
	v_cmp_gt_f32_e32 vcc, s96, v34
	v_mul_f32_e32 v152, 0x4f800000, v34
	s_nop 0
	v_cndmask_b32_e32 v34, v34, v152, vcc
	v_sqrt_f32_e32 v152, v34
	s_nop 0
	v_add_u32_e32 v153, -1, v152
	v_fma_f32 v154, -v153, v152, v34
	v_cmp_ge_f32_e64 s[6:7], 0, v154
	v_add_u32_e32 v154, 1, v152
	s_nop 0
	v_cndmask_b32_e64 v153, v152, v153, s[6:7]
	v_fma_f32 v152, -v154, v152, v34
	v_cmp_lt_f32_e64 s[6:7], 0, v152
	s_nop 1
	v_cndmask_b32_e64 v152, v153, v154, s[6:7]
	v_mul_f32_e32 v153, 0x37800000, v152
	v_cndmask_b32_e32 v152, v152, v153, vcc
	v_cmp_class_f32_e32 vcc, v34, v173
	s_nop 1
	v_cndmask_b32_e32 v34, v152, v34, vcc
	v_div_scale_f32 v152, s[6:7], v34, v34, 1.0
	v_rcp_f32_e32 v153, v152
	s_nop 0
	v_fma_f32 v154, -v152, v153, 1.0
	v_fmac_f32_e32 v153, v154, v153
	v_div_scale_f32 v154, vcc, 1.0, v34, 1.0
	v_mul_f32_e32 v155, v154, v153
	v_fma_f32 v156, -v152, v155, v154
	v_fmac_f32_e32 v155, v156, v153
	v_fma_f32 v152, -v152, v155, v154
	v_div_fmas_f32 v152, v152, v153, v155
	v_div_fixup_f32 v201, v152, v34, 1.0
	v_add_u32_e32 v152, 0xa0, v140
	v_ashrrev_i32_e32 v153, 31, v152
	v_lshlrev_b64 v[154:155], 6, v[152:153]
	v_lshl_add_u64 v[154:155], s[30:31], 0, v[154:155]
	v_mul_f32_e32 v164, 0x3f553b94, v201
	s_waitcnt vmcnt(2)
	v_pk_add_f32 v[162:163], v[218:219], v[222:223]
	v_pk_add_f32 v[166:167], v[216:217], v[220:221]
	s_waitcnt vmcnt(0)
	v_pk_add_f32 v[154:155], v[226:227], v[230:231]
	v_pk_add_f32 v[158:159], v[224:225], v[228:229]
	global_load_dwordx4 v[216:219], v[234:235], off offset:3104
	global_load_dwordx4 v[220:223], v[234:235], off offset:3120
	global_load_dwordx4 v[224:227], v[234:235], off offset:3072
	global_load_dwordx4 v[228:231], v[234:235], off offset:3088
	v_pk_add_f32 v[154:155], v[154:155], v[162:163]
	v_pk_add_f32 v[158:159], v[158:159], v[166:167]
	v_add_f32_e32 v154, v154, v155
	v_add_f32_e32 v34, v158, v159
	v_add_f32_e32 v34, v34, v154
	v_fmamk_f32 v34, v34, 0x3b000000, v169
	v_cmp_gt_f32_e32 vcc, s96, v34
	v_mul_f32_e32 v154, 0x4f800000, v34
	s_nop 0
	v_cndmask_b32_e32 v34, v34, v154, vcc
	v_sqrt_f32_e32 v154, v34
	s_nop 0
	v_add_u32_e32 v155, -1, v154
	v_fma_f32 v156, -v155, v154, v34
	v_cmp_ge_f32_e64 s[6:7], 0, v156
	v_add_u32_e32 v156, 1, v154
	s_nop 0
	v_cndmask_b32_e64 v155, v154, v155, s[6:7]
	v_fma_f32 v154, -v156, v154, v34
	v_cmp_lt_f32_e64 s[6:7], 0, v154
	s_nop 1
	v_cndmask_b32_e64 v154, v155, v156, s[6:7]
	v_mul_f32_e32 v155, 0x37800000, v154
	v_cndmask_b32_e32 v154, v154, v155, vcc
	v_cmp_class_f32_e32 vcc, v34, v173
	s_nop 1
	v_cndmask_b32_e32 v34, v154, v34, vcc
	v_div_scale_f32 v154, s[6:7], v34, v34, 1.0
	v_rcp_f32_e32 v155, v154
	s_nop 0
	v_fma_f32 v156, -v154, v155, 1.0
	v_fmac_f32_e32 v155, v156, v155
	v_div_scale_f32 v156, vcc, 1.0, v34, 1.0
	v_mul_f32_e32 v158, v156, v155
	v_fma_f32 v159, -v154, v158, v156
	v_fmac_f32_e32 v158, v159, v155
	v_fma_f32 v154, -v154, v158, v156
	v_div_fmas_f32 v154, v154, v155, v158
	v_div_fixup_f32 v204, v154, v34, 1.0
	v_add_u32_e32 v154, 0xb0, v140
	v_ashrrev_i32_e32 v155, 31, v154
	v_lshlrev_b64 v[158:159], 6, v[154:155]
	v_lshl_add_u64 v[158:159], s[30:31], 0, v[158:159]
	s_waitcnt vmcnt(2)
	v_pk_add_f32 v[166:167], v[218:219], v[222:223]
	v_pk_add_f32 v[170:171], v[216:217], v[220:221]
	s_waitcnt vmcnt(0)
	v_pk_add_f32 v[158:159], v[226:227], v[230:231]
	v_pk_add_f32 v[162:163], v[224:225], v[228:229]
	v_pk_add_f32 v[158:159], v[158:159], v[166:167]
	v_pk_add_f32 v[162:163], v[162:163], v[170:171]
	v_add_f32_e32 v156, v158, v159
	v_add_f32_e32 v34, v162, v163
	v_add_f32_e32 v34, v34, v156
	v_fmamk_f32 v34, v34, 0x3b000000, v169
	v_cmp_gt_f32_e32 vcc, s96, v34
	v_mul_f32_e32 v156, 0x4f800000, v34
	v_lshlrev_b64 v[186:187], 7, v[140:141]
	v_cndmask_b32_e32 v34, v34, v156, vcc
	v_sqrt_f32_e32 v156, v34
	v_lshlrev_b64 v[170:171], 7, v[148:149]
	v_lshlrev_b64 v[166:167], 7, v[150:151]
	v_add_u32_e32 v158, -1, v156
	v_fma_f32 v159, -v158, v156, v34
	v_cmp_ge_f32_e64 s[6:7], 0, v159
	v_add_u32_e32 v159, 1, v156
	s_nop 0
	v_cndmask_b32_e64 v158, v156, v158, s[6:7]
	v_fma_f32 v156, -v159, v156, v34
	v_cmp_lt_f32_e64 s[6:7], 0, v156
	s_nop 1
	v_cndmask_b32_e64 v156, v158, v159, s[6:7]
	v_mul_f32_e32 v158, 0x37800000, v156
	v_cndmask_b32_e32 v156, v156, v158, vcc
	v_cmp_class_f32_e32 vcc, v34, v173
	s_nop 1
	v_cndmask_b32_e32 v34, v156, v34, vcc
	v_div_scale_f32 v156, s[6:7], v34, v34, 1.0
	v_rcp_f32_e32 v158, v156
	s_nop 0
	v_fma_f32 v159, -v156, v158, 1.0
	v_fmac_f32_e32 v158, v159, v158
	v_div_scale_f32 v159, vcc, 1.0, v34, 1.0
	v_mul_f32_e32 v160, v159, v158
	v_fma_f32 v162, -v156, v160, v159
	v_fmac_f32_e32 v160, v162, v158
	v_fma_f32 v156, -v156, v160, v159
	v_div_fmas_f32 v156, v156, v158, v160
	v_div_fixup_f32 v207, v156, v34, 1.0
	v_lshl_or_b32 v34, v199, 3, s2
	v_or_b32_e32 v208, s92, v34
	v_mul_hi_i32 v34, v208, s97
	v_lshrrev_b32_e32 v156, 31, v34
	v_lshrrev_b32_e32 v34, 5, v34
	v_add_u32_e32 v34, v34, v156
	v_mul_lo_u32 v192, v34, s28
	v_sub_u32_e32 v188, v208, v192
	v_cmp_lt_i32_e32 vcc, s29, v188
	v_ashrrev_i32_e32 v193, 31, v192
	v_mul_f32_e32 v160, 0x3f553b94, v204
	v_lshlrev_b64 v[162:163], 7, v[152:153]
	v_mul_f32_e32 v156, 0x3f553b94, v207
	v_lshlrev_b64 v[158:159], 7, v[154:155]
	s_and_saveexec_b64 s[6:7], vcc
	s_xor_b64 s[6:7], exec, s[6:7]
	s_cbranch_execz .LBB0_575
	v_add_u32_e32 v34, 0xffffff80, v188
	v_lshrrev_b32_e32 v34, 1, v34
	v_lshlrev_b64 v[188:189], 2, v[34:35]
	v_lshl_add_u64 v[190:191], s[16:17], 0, v[188:189]
	v_lshl_add_u64 v[194:195], v[190:191], 0, v[186:187]
	global_load_dwordx4 v[210:213], v[194:195], off
	v_lshl_add_u64 v[194:195], s[14:15], 0, v[188:189]
	v_lshl_add_u64 v[188:189], v[194:195], 0, v[186:187]
	global_load_dwordx4 v[214:217], v[188:189], off
	v_pk_mul_f32 v[222:223], v[22:23], v[184:185] op_sel_hi:[1,0]
	v_pk_mul_f32 v[218:219], v[18:19], v[184:185] op_sel_hi:[1,0]
	v_mov_b32_e32 v141, v35
	v_mov_b32_e32 v143, v35
	v_pk_mul_f32 v[220:221], v[24:25], v[184:185] op_sel_hi:[1,0]
	v_lshl_add_u64 v[188:189], v[192:193], 1, s[26:27]
	v_pk_mul_f32 v[192:193], v[20:21], v[184:185] op_sel_hi:[1,0]
	v_mad_i64_i32 v[224:225], s[12:13], v140, s10, v[188:189]
	s_waitcnt vmcnt(1)
	v_pk_mul_f32 v[228:229], v[222:223], v[210:211]
	v_pk_mul_f32 v[210:211], v[218:219], v[210:211]
	v_pk_mul_f32 v[226:227], v[220:221], v[212:213]
	s_waitcnt vmcnt(0)
	v_pk_fma_f32 v[218:219], v[218:219], v[214:215], v[228:229] neg_lo:[0,0,1] neg_hi:[0,0,1]
	v_pk_fma_f32 v[210:211], v[222:223], v[214:215], v[210:211]
	v_cvt_pk_fp8_f32 v141, v218, v219
	v_cvt_pk_fp8_f32 v143, v210, v211
	v_pk_mul_f32 v[212:213], v[192:193], v[212:213]
	v_pk_fma_f32 v[192:193], v[192:193], v[216:217], v[226:227] neg_lo:[0,0,1] neg_hi:[0,0,1]
	v_pk_fma_f32 v[210:211], v[220:221], v[216:217], v[212:213]
	v_cvt_pk_fp8_f32 v141, v192, v193 op_sel:[0,0,1]
	v_cvt_pk_fp8_f32 v143, v210, v211 op_sel:[0,0,1]
	v_lshl_add_u64 v[192:193], v[224:225], 0, v[34:35]
	v_lshl_add_u64 v[210:211], v[190:191], 0, v[182:183]
	global_store_dword v[192:193], v141, off offset:256
	global_store_dword v[192:193], v143, off offset:288
	global_load_dwordx4 v[210:213], v[210:211], off
	v_lshl_add_u64 v[192:193], v[194:195], 0, v[182:183]
	global_load_dwordx4 v[214:217], v[192:193], off
	v_pk_mul_f32 v[222:223], v[30:31], v[180:181] op_sel_hi:[1,0]
	v_pk_mul_f32 v[218:219], v[26:27], v[180:181] op_sel_hi:[1,0]
	v_mov_b32_e32 v141, v35
	v_mov_b32_e32 v143, v35
	v_pk_mul_f32 v[220:221], v[32:33], v[180:181] op_sel_hi:[1,0]
	v_pk_mul_f32 v[192:193], v[28:29], v[180:181] op_sel_hi:[1,0]
	v_mad_i64_i32 v[224:225], s[12:13], v142, s10, v[188:189]
	s_waitcnt vmcnt(1)
	v_pk_mul_f32 v[228:229], v[222:223], v[210:211]
	v_pk_mul_f32 v[210:211], v[218:219], v[210:211]
	s_waitcnt vmcnt(0)
	v_pk_fma_f32 v[218:219], v[218:219], v[214:215], v[228:229] neg_lo:[0,0,1] neg_hi:[0,0,1]
	v_pk_fma_f32 v[210:211], v[222:223], v[214:215], v[210:211]
	v_cvt_pk_fp8_f32 v141, v218, v219
	v_cvt_pk_fp8_f32 v143, v210, v211
	v_pk_mul_f32 v[226:227], v[220:221], v[212:213]
	v_pk_mul_f32 v[212:213], v[192:193], v[212:213]
	v_pk_fma_f32 v[192:193], v[192:193], v[216:217], v[226:227] neg_lo:[0,0,1] neg_hi:[0,0,1]
	v_pk_fma_f32 v[210:211], v[220:221], v[216:217], v[212:213]
	v_cvt_pk_fp8_f32 v141, v192, v193 op_sel:[0,0,1]
	v_cvt_pk_fp8_f32 v143, v210, v211 op_sel:[0,0,1]
	v_lshl_add_u64 v[192:193], v[224:225], 0, v[34:35]
	v_lshl_add_u64 v[210:211], v[190:191], 0, v[178:179]
	global_store_dword v[192:193], v141, off offset:256
	global_store_dword v[192:193], v143, off offset:288
	global_load_dwordx4 v[210:213], v[210:211], off
	v_lshl_add_u64 v[192:193], v[194:195], 0, v[178:179]
	global_load_dwordx4 v[214:217], v[192:193], off
	v_pk_mul_f32 v[222:223], v[6:7], v[176:177] op_sel_hi:[1,0]
	v_pk_mul_f32 v[218:219], v[2:3], v[176:177] op_sel_hi:[1,0]
	v_mov_b32_e32 v141, v35
	v_mov_b32_e32 v143, v35
	v_pk_mul_f32 v[220:221], v[8:9], v[176:177] op_sel_hi:[1,0]
	v_pk_mul_f32 v[192:193], v[4:5], v[176:177] op_sel_hi:[1,0]
	v_mad_i64_i32 v[224:225], s[12:13], v144, s10, v[188:189]
	s_waitcnt vmcnt(1)
	v_pk_mul_f32 v[228:229], v[222:223], v[210:211]
	v_pk_mul_f32 v[210:211], v[218:219], v[210:211]
	s_waitcnt vmcnt(0)
	v_pk_fma_f32 v[218:219], v[218:219], v[214:215], v[228:229] neg_lo:[0,0,1] neg_hi:[0,0,1]
	v_pk_fma_f32 v[210:211], v[222:223], v[214:215], v[210:211]
	v_cvt_pk_fp8_f32 v141, v218, v219
	v_cvt_pk_fp8_f32 v143, v210, v211
	v_pk_mul_f32 v[226:227], v[220:221], v[212:213]
	v_pk_mul_f32 v[212:213], v[192:193], v[212:213]
	v_pk_fma_f32 v[192:193], v[192:193], v[216:217], v[226:227] neg_lo:[0,0,1] neg_hi:[0,0,1]
	v_pk_fma_f32 v[210:211], v[220:221], v[216:217], v[212:213]
	v_cvt_pk_fp8_f32 v141, v192, v193 op_sel:[0,0,1]
	v_cvt_pk_fp8_f32 v143, v210, v211 op_sel:[0,0,1]
	v_lshl_add_u64 v[192:193], v[224:225], 0, v[34:35]
	v_lshl_add_u64 v[210:211], v[190:191], 0, v[174:175]
	global_store_dword v[192:193], v141, off offset:256
	global_store_dword v[192:193], v143, off offset:288
	global_load_dwordx4 v[210:213], v[210:211], off
	v_lshl_add_u64 v[192:193], v[194:195], 0, v[174:175]
	global_load_dwordx4 v[214:217], v[192:193], off
	v_pk_mul_f32 v[222:223], v[14:15], v[172:173] op_sel_hi:[1,0]
	v_pk_mul_f32 v[218:219], v[10:11], v[172:173] op_sel_hi:[1,0]
	v_mov_b32_e32 v141, v35
	v_mov_b32_e32 v143, v35
	v_pk_mul_f32 v[220:221], v[16:17], v[172:173] op_sel_hi:[1,0]
	v_pk_mul_f32 v[192:193], v[12:13], v[172:173] op_sel_hi:[1,0]
	v_mad_i64_i32 v[224:225], s[12:13], v146, s10, v[188:189]
	s_waitcnt vmcnt(1)
	v_pk_mul_f32 v[228:229], v[222:223], v[210:211]
	v_pk_mul_f32 v[210:211], v[218:219], v[210:211]
	s_waitcnt vmcnt(0)
	v_pk_fma_f32 v[218:219], v[218:219], v[214:215], v[228:229] neg_lo:[0,0,1] neg_hi:[0,0,1]
	v_pk_fma_f32 v[210:211], v[222:223], v[214:215], v[210:211]
	v_cvt_pk_fp8_f32 v141, v218, v219
	v_cvt_pk_fp8_f32 v143, v210, v211
	v_pk_mul_f32 v[226:227], v[220:221], v[212:213]
	v_pk_mul_f32 v[212:213], v[192:193], v[212:213]
	v_pk_fma_f32 v[192:193], v[192:193], v[216:217], v[226:227] neg_lo:[0,0,1] neg_hi:[0,0,1]
	v_pk_fma_f32 v[210:211], v[220:221], v[216:217], v[212:213]
	v_cvt_pk_fp8_f32 v141, v192, v193 op_sel:[0,0,1]
	v_cvt_pk_fp8_f32 v143, v210, v211 op_sel:[0,0,1]
	v_lshl_add_u64 v[192:193], v[224:225], 0, v[34:35]
	v_lshl_add_u64 v[210:211], v[190:191], 0, v[170:171]
	global_store_dword v[192:193], v141, off offset:256
	global_store_dword v[192:193], v143, off offset:288
	global_load_dwordx4 v[210:213], v[210:211], off
	v_lshl_add_u64 v[192:193], v[194:195], 0, v[170:171]
	global_load_dwordx4 v[214:217], v[192:193], off
	v_pk_mul_f32 v[222:223], v[120:121], v[168:169] op_sel_hi:[1,0]
	v_pk_mul_f32 v[218:219], v[116:117], v[168:169] op_sel_hi:[1,0]
	v_mov_b32_e32 v141, v35
	v_mov_b32_e32 v143, v35
	v_pk_mul_f32 v[220:221], v[122:123], v[168:169] op_sel_hi:[1,0]
	v_pk_mul_f32 v[192:193], v[118:119], v[168:169] op_sel_hi:[1,0]
	v_mad_i64_i32 v[224:225], s[12:13], v148, s10, v[188:189]
	s_waitcnt vmcnt(1)
	v_pk_mul_f32 v[228:229], v[222:223], v[210:211]
	v_pk_mul_f32 v[210:211], v[218:219], v[210:211]
	s_waitcnt vmcnt(0)
	v_pk_fma_f32 v[218:219], v[218:219], v[214:215], v[228:229] neg_lo:[0,0,1] neg_hi:[0,0,1]
	v_pk_fma_f32 v[210:211], v[222:223], v[214:215], v[210:211]
	v_cvt_pk_fp8_f32 v141, v218, v219
	v_cvt_pk_fp8_f32 v143, v210, v211
	v_pk_mul_f32 v[226:227], v[220:221], v[212:213]
	v_pk_mul_f32 v[212:213], v[192:193], v[212:213]
	v_pk_fma_f32 v[192:193], v[192:193], v[216:217], v[226:227] neg_lo:[0,0,1] neg_hi:[0,0,1]
	v_pk_fma_f32 v[210:211], v[220:221], v[216:217], v[212:213]
	v_cvt_pk_fp8_f32 v141, v192, v193 op_sel:[0,0,1]
	v_cvt_pk_fp8_f32 v143, v210, v211 op_sel:[0,0,1]
	v_lshl_add_u64 v[192:193], v[224:225], 0, v[34:35]
	v_lshl_add_u64 v[210:211], v[190:191], 0, v[166:167]
	global_store_dword v[192:193], v141, off offset:256
	global_store_dword v[192:193], v143, off offset:288
	global_load_dwordx4 v[210:213], v[210:211], off
	v_lshl_add_u64 v[192:193], v[194:195], 0, v[166:167]
	global_load_dwordx4 v[214:217], v[192:193], off
	v_pk_mul_f32 v[222:223], v[128:129], v[164:165] op_sel_hi:[1,0]
	v_pk_mul_f32 v[218:219], v[124:125], v[164:165] op_sel_hi:[1,0]
	v_mov_b32_e32 v141, v35
	v_mov_b32_e32 v143, v35
	v_pk_mul_f32 v[220:221], v[130:131], v[164:165] op_sel_hi:[1,0]
	v_pk_mul_f32 v[192:193], v[126:127], v[164:165] op_sel_hi:[1,0]
	v_mad_i64_i32 v[224:225], s[12:13], v150, s10, v[188:189]
	s_waitcnt vmcnt(1)
	v_pk_mul_f32 v[228:229], v[222:223], v[210:211]
	v_pk_mul_f32 v[210:211], v[218:219], v[210:211]
	s_waitcnt vmcnt(0)
	v_pk_fma_f32 v[218:219], v[218:219], v[214:215], v[228:229] neg_lo:[0,0,1] neg_hi:[0,0,1]
	v_pk_fma_f32 v[210:211], v[222:223], v[214:215], v[210:211]
	v_cvt_pk_fp8_f32 v141, v218, v219
	v_cvt_pk_fp8_f32 v143, v210, v211
	v_pk_mul_f32 v[226:227], v[220:221], v[212:213]
	v_pk_mul_f32 v[212:213], v[192:193], v[212:213]
	v_pk_fma_f32 v[192:193], v[192:193], v[216:217], v[226:227] neg_lo:[0,0,1] neg_hi:[0,0,1]
	v_pk_fma_f32 v[210:211], v[220:221], v[216:217], v[212:213]
	v_cvt_pk_fp8_f32 v141, v192, v193 op_sel:[0,0,1]
	v_cvt_pk_fp8_f32 v143, v210, v211 op_sel:[0,0,1]
	v_lshl_add_u64 v[192:193], v[224:225], 0, v[34:35]
	v_lshl_add_u64 v[210:211], v[190:191], 0, v[162:163]
	global_store_dword v[192:193], v141, off offset:256
	global_store_dword v[192:193], v143, off offset:288
	global_load_dwordx4 v[210:213], v[210:211], off
	v_lshl_add_u64 v[192:193], v[194:195], 0, v[162:163]
	global_load_dwordx4 v[214:217], v[192:193], off
	v_pk_mul_f32 v[222:223], v[104:105], v[160:161] op_sel_hi:[1,0]
	v_pk_mul_f32 v[218:219], v[100:101], v[160:161] op_sel_hi:[1,0]
	v_mov_b32_e32 v141, v35
	v_mov_b32_e32 v143, v35
	v_pk_mul_f32 v[220:221], v[106:107], v[160:161] op_sel_hi:[1,0]
	v_pk_mul_f32 v[192:193], v[102:103], v[160:161] op_sel_hi:[1,0]
	v_mad_i64_i32 v[224:225], s[12:13], v152, s10, v[188:189]
	v_lshl_add_u64 v[190:191], v[190:191], 0, v[158:159]
	v_lshl_add_u64 v[194:195], v[194:195], 0, v[158:159]
	v_mad_i64_i32 v[188:189], s[12:13], v154, s10, v[188:189]
	v_lshl_add_u64 v[188:189], v[188:189], 0, v[34:35]
	s_waitcnt vmcnt(1)
	v_pk_mul_f32 v[228:229], v[222:223], v[210:211]
	v_pk_mul_f32 v[210:211], v[218:219], v[210:211]
	s_waitcnt vmcnt(0)
	v_pk_fma_f32 v[218:219], v[218:219], v[214:215], v[228:229] neg_lo:[0,0,1] neg_hi:[0,0,1]
	v_pk_fma_f32 v[210:211], v[222:223], v[214:215], v[210:211]
	v_cvt_pk_fp8_f32 v141, v218, v219
	v_cvt_pk_fp8_f32 v143, v210, v211
	v_pk_mul_f32 v[226:227], v[220:221], v[212:213]
	v_pk_mul_f32 v[212:213], v[192:193], v[212:213]
	v_pk_fma_f32 v[192:193], v[192:193], v[216:217], v[226:227] neg_lo:[0,0,1] neg_hi:[0,0,1]
	v_pk_fma_f32 v[210:211], v[220:221], v[216:217], v[212:213]
	v_cvt_pk_fp8_f32 v141, v192, v193 op_sel:[0,0,1]
	v_cvt_pk_fp8_f32 v143, v210, v211 op_sel:[0,0,1]
	v_lshl_add_u64 v[192:193], v[224:225], 0, v[34:35]
	global_store_dword v[192:193], v141, off offset:256
	global_store_dword v[192:193], v143, off offset:288
	global_load_dwordx4 v[190:193], v[190:191], off
	v_pk_mul_f32 v[218:219], v[112:113], v[156:157] op_sel_hi:[1,0]
	global_load_dwordx4 v[210:213], v[194:195], off
	v_pk_mul_f32 v[214:215], v[108:109], v[156:157] op_sel_hi:[1,0]
	v_mov_b32_e32 v141, v35
	v_mov_b32_e32 v143, v35
	v_pk_mul_f32 v[216:217], v[114:115], v[156:157] op_sel_hi:[1,0]
	v_pk_mul_f32 v[194:195], v[110:111], v[156:157] op_sel_hi:[1,0]
	s_waitcnt vmcnt(1)
	v_pk_mul_f32 v[222:223], v[218:219], v[190:191]
	v_pk_mul_f32 v[190:191], v[214:215], v[190:191]
	s_waitcnt vmcnt(0)
	v_pk_fma_f32 v[214:215], v[214:215], v[210:211], v[222:223] neg_lo:[0,0,1] neg_hi:[0,0,1]
	v_pk_fma_f32 v[190:191], v[218:219], v[210:211], v[190:191]
	v_cvt_pk_fp8_f32 v141, v214, v215
	v_cvt_pk_fp8_f32 v143, v190, v191
	v_pk_mul_f32 v[220:221], v[216:217], v[192:193]
	v_pk_mul_f32 v[192:193], v[194:195], v[192:193]
	v_pk_fma_f32 v[190:191], v[194:195], v[212:213], v[220:221] neg_lo:[0,0,1] neg_hi:[0,0,1]
	v_pk_fma_f32 v[192:193], v[216:217], v[212:213], v[192:193]
	v_cvt_pk_fp8_f32 v141, v190, v191 op_sel:[0,0,1]
	v_cvt_pk_fp8_f32 v143, v192, v193 op_sel:[0,0,1]
	global_store_dword v[188:189], v141, off offset:256
	global_store_dword v[188:189], v143, off offset:288

.LBB0_1596:
	v_mov_b32_e32 v34, v0
	s_lshl_b32 s4, s6, 8
	s_add_i32 s4, s4, s90
	v_and_b32_e32 v139, 15, v34
	v_or_b32_e32 v140, s4, v139
	v_ashrrev_i32_e32 v141, 31, v140
	v_lshlrev_b64 v[142:143], 6, v[140:141]
	v_lshl_add_u64 v[154:155], s[26:27], 0, v[142:143]
	s_mov_b32 s100, 0x2000
	s_mov_b32 s101, 0
	v_mov_b64_e32 v[232:233], v[154:155]
	v_lshl_add_u64 v[234:235], v[154:155], 0, s[100:101]
	global_load_dwordx4 v[216:219], v[232:233], off offset:32
	global_load_dwordx4 v[220:223], v[232:233], off offset:48
	global_load_dwordx4 v[224:227], v[232:233], off
	global_load_dwordx4 v[228:231], v[232:233], off offset:16
	v_bfe_u32 v199, v34, 4, 2
	s_lshl_b32 s2, s2, 8
	s_waitcnt vmcnt(0)
	v_pk_add_f32 v[144:145], v[218:219], v[222:223]
	v_pk_add_f32 v[142:143], v[216:217], v[220:221]
	v_pk_add_f32 v[152:153], v[226:227], v[230:231]
	v_pk_add_f32 v[150:151], v[224:225], v[228:229]
	global_load_dwordx4 v[216:219], v[232:233], off offset:1056
	global_load_dwordx4 v[220:223], v[232:233], off offset:1072
	global_load_dwordx4 v[224:227], v[232:233], off offset:1024
	global_load_dwordx4 v[228:231], v[232:233], off offset:1040
	v_pk_add_f32 v[144:145], v[152:153], v[144:145]
	v_pk_add_f32 v[142:143], v[150:151], v[142:143]
	s_nop 0
	v_add_f32_e32 v34, v142, v143
	v_add_f32_e32 v142, v144, v145
	v_add_f32_e32 v34, v34, v142
	v_fmamk_f32 v34, v34, 0x3b000000, v169
	v_cmp_gt_f32_e32 vcc, s95, v34
	v_mul_f32_e32 v142, 0x4f800000, v34
	s_nop 0
	v_cndmask_b32_e32 v34, v34, v142, vcc
	v_sqrt_f32_e32 v142, v34
	s_nop 0
	v_add_u32_e32 v143, -1, v142
	v_fma_f32 v144, -v143, v142, v34
	v_cmp_ge_f32_e64 s[6:7], 0, v144
	v_add_u32_e32 v144, 1, v142
	s_nop 0
	v_cndmask_b32_e64 v143, v142, v143, s[6:7]
	v_fma_f32 v142, -v144, v142, v34
	v_cmp_lt_f32_e64 s[6:7], 0, v142
	s_nop 1
	v_cndmask_b32_e64 v142, v143, v144, s[6:7]
	v_mul_f32_e32 v143, 0x37800000, v142
	v_cndmask_b32_e32 v142, v142, v143, vcc
	v_cmp_class_f32_e32 vcc, v34, v173
	s_nop 1
	v_cndmask_b32_e32 v34, v142, v34, vcc
	v_div_scale_f32 v142, s[6:7], v34, v34, 1.0
	v_rcp_f32_e32 v143, v142
	s_nop 0
	v_fma_f32 v144, -v142, v143, 1.0
	v_fmac_f32_e32 v143, v144, v143
	v_div_scale_f32 v144, vcc, 1.0, v34, 1.0
	v_mul_f32_e32 v145, v144, v143
	v_fma_f32 v146, -v142, v145, v144
	v_fmac_f32_e32 v145, v146, v143
	v_fma_f32 v142, -v142, v145, v144
	v_div_fmas_f32 v142, v142, v143, v145
	v_div_fixup_f32 v202, v142, v34, 1.0
	v_or_b32_e32 v142, 16, v140
	v_ashrrev_i32_e32 v143, 31, v142
	v_lshlrev_b64 v[144:145], 6, v[142:143]
	v_lshl_add_u64 v[158:159], s[26:27], 0, v[144:145]
	v_mul_f32_e32 v184, 0x3f553b94, v202
	v_lshlrev_b64 v[182:183], 7, v[142:143]
	s_waitcnt vmcnt(2)
	v_pk_add_f32 v[146:147], v[218:219], v[222:223]
	v_pk_add_f32 v[144:145], v[216:217], v[220:221]
	s_waitcnt vmcnt(0)
	v_pk_add_f32 v[154:155], v[226:227], v[230:231]
	v_pk_add_f32 v[152:153], v[224:225], v[228:229]
	global_load_dwordx4 v[216:219], v[232:233], off offset:2080
	global_load_dwordx4 v[220:223], v[232:233], off offset:2096
	global_load_dwordx4 v[224:227], v[232:233], off offset:2048
	global_load_dwordx4 v[228:231], v[232:233], off offset:2064
	v_pk_add_f32 v[146:147], v[154:155], v[146:147]
	v_pk_add_f32 v[144:145], v[152:153], v[144:145]
	s_nop 0
	v_add_f32_e32 v34, v144, v145
	v_add_f32_e32 v144, v146, v147
	v_add_f32_e32 v34, v34, v144
	v_fmamk_f32 v34, v34, 0x3b000000, v169
	v_cmp_gt_f32_e32 vcc, s95, v34
	v_mul_f32_e32 v144, 0x4f800000, v34
	s_nop 0
	v_cndmask_b32_e32 v34, v34, v144, vcc
	v_sqrt_f32_e32 v144, v34
	s_nop 0
	v_add_u32_e32 v145, -1, v144
	v_fma_f32 v146, -v145, v144, v34
	v_cmp_ge_f32_e64 s[6:7], 0, v146
	v_add_u32_e32 v146, 1, v144
	s_nop 0
	v_cndmask_b32_e64 v145, v144, v145, s[6:7]
	v_fma_f32 v144, -v146, v144, v34
	v_cmp_lt_f32_e64 s[6:7], 0, v144
	s_nop 1
	v_cndmask_b32_e64 v144, v145, v146, s[6:7]
	v_mul_f32_e32 v145, 0x37800000, v144
	v_cndmask_b32_e32 v144, v144, v145, vcc
	v_cmp_class_f32_e32 vcc, v34, v173
	s_nop 1
	v_cndmask_b32_e32 v34, v144, v34, vcc
	v_div_scale_f32 v144, s[6:7], v34, v34, 1.0
	v_rcp_f32_e32 v145, v144
	s_nop 0
	v_fma_f32 v146, -v144, v145, 1.0
	v_fmac_f32_e32 v145, v146, v145
	v_div_scale_f32 v146, vcc, 1.0, v34, 1.0
	v_mul_f32_e32 v147, v146, v145
	v_fma_f32 v148, -v144, v147, v146
	v_fmac_f32_e32 v147, v148, v145
	v_fma_f32 v144, -v144, v147, v146
	v_div_fmas_f32 v144, v144, v145, v147
	v_div_fixup_f32 v203, v144, v34, 1.0
	v_or_b32_e32 v144, 32, v140
	v_ashrrev_i32_e32 v145, 31, v144
	v_lshlrev_b64 v[146:147], 6, v[144:145]
	v_lshl_add_u64 v[154:155], s[26:27], 0, v[146:147]
	v_mul_f32_e32 v180, 0x3f553b94, v203
	v_lshlrev_b64 v[178:179], 7, v[144:145]
	s_waitcnt vmcnt(2)
	v_pk_add_f32 v[148:149], v[218:219], v[222:223]
	v_pk_add_f32 v[146:147], v[216:217], v[220:221]
	s_waitcnt vmcnt(0)
	v_pk_add_f32 v[154:155], v[226:227], v[230:231]
	v_pk_add_f32 v[158:159], v[224:225], v[228:229]
	global_load_dwordx4 v[216:219], v[232:233], off offset:3104
	global_load_dwordx4 v[220:223], v[232:233], off offset:3120
	global_load_dwordx4 v[224:227], v[232:233], off offset:3072
	global_load_dwordx4 v[228:231], v[232:233], off offset:3088
	v_pk_add_f32 v[148:149], v[154:155], v[148:149]
	v_pk_add_f32 v[146:147], v[158:159], v[146:147]
	s_nop 0
	v_add_f32_e32 v34, v146, v147
	v_add_f32_e32 v146, v148, v149
	v_add_f32_e32 v34, v34, v146
	v_fmamk_f32 v34, v34, 0x3b000000, v169
	v_cmp_gt_f32_e32 vcc, s95, v34
	v_mul_f32_e32 v146, 0x4f800000, v34
	s_nop 0
	v_cndmask_b32_e32 v34, v34, v146, vcc
	v_sqrt_f32_e32 v146, v34
	s_nop 0
	v_add_u32_e32 v147, -1, v146
	v_fma_f32 v148, -v147, v146, v34
	v_cmp_ge_f32_e64 s[6:7], 0, v148
	v_add_u32_e32 v148, 1, v146
	s_nop 0
	v_cndmask_b32_e64 v147, v146, v147, s[6:7]
	v_fma_f32 v146, -v148, v146, v34
	v_cmp_lt_f32_e64 s[6:7], 0, v146
	s_nop 1
	v_cndmask_b32_e64 v146, v147, v148, s[6:7]
	v_mul_f32_e32 v147, 0x37800000, v146
	v_cndmask_b32_e32 v146, v146, v147, vcc
	v_cmp_class_f32_e32 vcc, v34, v173
	s_nop 1
	v_cndmask_b32_e32 v34, v146, v34, vcc
	v_div_scale_f32 v146, s[6:7], v34, v34, 1.0
	v_rcp_f32_e32 v147, v146
	s_nop 0
	v_fma_f32 v148, -v146, v147, 1.0
	v_fmac_f32_e32 v147, v148, v147
	v_div_scale_f32 v148, vcc, 1.0, v34, 1.0
	v_mul_f32_e32 v149, v148, v147
	v_fma_f32 v150, -v146, v149, v148
	v_fmac_f32_e32 v149, v150, v147
	v_fma_f32 v146, -v146, v149, v148
	v_div_fmas_f32 v146, v146, v147, v149
	v_div_fixup_f32 v205, v146, v34, 1.0
	v_or_b32_e32 v146, 48, v140
	v_ashrrev_i32_e32 v147, 31, v146
	v_lshlrev_b64 v[148:149], 6, v[146:147]
	v_lshl_add_u64 v[158:159], s[26:27], 0, v[148:149]
	v_mul_f32_e32 v176, 0x3f553b94, v205
	v_lshlrev_b64 v[174:175], 7, v[146:147]
	s_waitcnt vmcnt(2)
	v_pk_add_f32 v[150:151], v[218:219], v[222:223]
	v_pk_add_f32 v[148:149], v[216:217], v[220:221]
	s_waitcnt vmcnt(0)
	v_pk_add_f32 v[158:159], v[226:227], v[230:231]
	v_pk_add_f32 v[162:163], v[224:225], v[228:229]
	global_load_dwordx4 v[216:219], v[234:235], off offset:32
	global_load_dwordx4 v[220:223], v[234:235], off offset:48
	global_load_dwordx4 v[224:227], v[234:235], off
	global_load_dwordx4 v[228:231], v[234:235], off offset:16
	v_pk_add_f32 v[150:151], v[158:159], v[150:151]
	v_pk_add_f32 v[148:149], v[162:163], v[148:149]
	s_nop 0
	v_add_f32_e32 v34, v148, v149
	v_add_f32_e32 v148, v150, v151
	v_add_f32_e32 v34, v34, v148
	v_fmamk_f32 v34, v34, 0x3b000000, v169
	v_cmp_gt_f32_e32 vcc, s95, v34
	v_mul_f32_e32 v148, 0x4f800000, v34
	s_nop 0
	v_cndmask_b32_e32 v34, v34, v148, vcc
	v_sqrt_f32_e32 v148, v34
	s_nop 0
	v_add_u32_e32 v149, -1, v148
	v_fma_f32 v150, -v149, v148, v34
	v_cmp_ge_f32_e64 s[6:7], 0, v150
	v_add_u32_e32 v150, 1, v148
	s_nop 0
	v_cndmask_b32_e64 v149, v148, v149, s[6:7]
	v_fma_f32 v148, -v150, v148, v34
	v_cmp_lt_f32_e64 s[6:7], 0, v148
	s_nop 1
	v_cndmask_b32_e64 v148, v149, v150, s[6:7]
	v_mul_f32_e32 v149, 0x37800000, v148
	v_cndmask_b32_e32 v148, v148, v149, vcc
	v_cmp_class_f32_e32 vcc, v34, v173
	s_nop 1
	v_cndmask_b32_e32 v34, v148, v34, vcc
	v_div_scale_f32 v148, s[6:7], v34, v34, 1.0
	v_rcp_f32_e32 v149, v148
	s_nop 0
	v_fma_f32 v150, -v148, v149, 1.0
	v_fmac_f32_e32 v149, v150, v149
	v_div_scale_f32 v150, vcc, 1.0, v34, 1.0
	v_mul_f32_e32 v151, v150, v149
	v_fma_f32 v152, -v148, v151, v150
	v_fmac_f32_e32 v151, v152, v149
	v_fma_f32 v148, -v148, v151, v150
	v_div_fmas_f32 v148, v148, v149, v151
	v_div_fixup_f32 v206, v148, v34, 1.0
	v_add_u32_e32 v148, 0x80, v140
	v_ashrrev_i32_e32 v149, 31, v148
	v_lshlrev_b64 v[150:151], 6, v[148:149]
	v_lshl_add_u64 v[154:155], s[26:27], 0, v[150:151]
	v_mul_f32_e32 v172, 0x3f553b94, v206
	s_waitcnt vmcnt(2)
	v_pk_add_f32 v[152:153], v[218:219], v[222:223]
	v_pk_add_f32 v[150:151], v[216:217], v[220:221]
	s_waitcnt vmcnt(0)
	v_pk_add_f32 v[154:155], v[226:227], v[230:231]
	v_pk_add_f32 v[158:159], v[224:225], v[228:229]
	global_load_dwordx4 v[216:219], v[234:235], off offset:1056
	global_load_dwordx4 v[220:223], v[234:235], off offset:1072
	global_load_dwordx4 v[224:227], v[234:235], off offset:1024
	global_load_dwordx4 v[228:231], v[234:235], off offset:1040
	v_pk_add_f32 v[152:153], v[154:155], v[152:153]
	v_pk_add_f32 v[150:151], v[158:159], v[150:151]
	s_nop 0
	v_add_f32_e32 v34, v150, v151
	v_add_f32_e32 v150, v152, v153
	v_add_f32_e32 v34, v34, v150
	v_fmamk_f32 v34, v34, 0x3b000000, v169
	v_cmp_gt_f32_e32 vcc, s95, v34
	v_mul_f32_e32 v150, 0x4f800000, v34
	s_nop 0
	v_cndmask_b32_e32 v34, v34, v150, vcc
	v_sqrt_f32_e32 v150, v34
	s_nop 0
	v_add_u32_e32 v151, -1, v150
	v_fma_f32 v152, -v151, v150, v34
	v_cmp_ge_f32_e64 s[6:7], 0, v152
	v_add_u32_e32 v152, 1, v150
	s_nop 0
	v_cndmask_b32_e64 v151, v150, v151, s[6:7]
	v_fma_f32 v150, -v152, v150, v34
	v_cmp_lt_f32_e64 s[6:7], 0, v150
	s_nop 1
	v_cndmask_b32_e64 v150, v151, v152, s[6:7]
	v_mul_f32_e32 v151, 0x37800000, v150
	v_cndmask_b32_e32 v150, v150, v151, vcc
	v_cmp_class_f32_e32 vcc, v34, v173
	s_nop 1
	v_cndmask_b32_e32 v34, v150, v34, vcc
	v_div_scale_f32 v150, s[6:7], v34, v34, 1.0
	v_rcp_f32_e32 v151, v150
	s_nop 0
	v_fma_f32 v152, -v150, v151, 1.0
	v_fmac_f32_e32 v151, v152, v151
	v_div_scale_f32 v152, vcc, 1.0, v34, 1.0
	v_mul_f32_e32 v153, v152, v151
	v_fma_f32 v154, -v150, v153, v152
	v_fmac_f32_e32 v153, v154, v151
	v_fma_f32 v150, -v150, v153, v152
	v_div_fmas_f32 v150, v150, v151, v153
	v_div_fixup_f32 v200, v150, v34, 1.0
	v_add_u32_e32 v150, 0x90, v140
	v_ashrrev_i32_e32 v151, 31, v150
	v_lshlrev_b64 v[152:153], 6, v[150:151]
	v_lshl_add_u64 v[158:159], s[26:27], 0, v[152:153]
	v_mul_f32_e32 v168, 0x3f553b94, v200
	s_waitcnt vmcnt(2)
	v_pk_add_f32 v[154:155], v[218:219], v[222:223]
	v_pk_add_f32 v[152:153], v[216:217], v[220:221]
	s_waitcnt vmcnt(0)
	v_pk_add_f32 v[158:159], v[226:227], v[230:231]
	v_pk_add_f32 v[162:163], v[224:225], v[228:229]
	global_load_dwordx4 v[216:219], v[234:235], off offset:2080
	global_load_dwordx4 v[220:223], v[234:235], off offset:2096
	global_load_dwordx4 v[224:227], v[234:235], off offset:2048
	global_load_dwordx4 v[228:231], v[234:235], off offset:2064
	v_pk_add_f32 v[154:155], v[158:159], v[154:155]
	v_pk_add_f32 v[152:153], v[162:163], v[152:153]
	s_nop 0
	v_add_f32_e32 v34, v152, v153
	v_add_f32_e32 v152, v154, v155
	v_add_f32_e32 v34, v34, v152
	v_fmamk_f32 v34, v34, 0x3b000000, v169
	v_cmp_gt_f32_e32 vcc, s95, v34
	v_mul_f32_e32 v152, 0x4f800000, v34
	s_nop 0
	v_cndmask_b32_e32 v34, v34, v152, vcc
	v_sqrt_f32_e32 v152, v34
	s_nop 0
	v_add_u32_e32 v153, -1, v152
	v_fma_f32 v154, -v153, v152, v34
	v_cmp_ge_f32_e64 s[6:7], 0, v154
	v_add_u32_e32 v154, 1, v152
	s_nop 0
	v_cndmask_b32_e64 v153, v152, v153, s[6:7]
	v_fma_f32 v152, -v154, v152, v34
	v_cmp_lt_f32_e64 s[6:7], 0, v152
	s_nop 1
	v_cndmask_b32_e64 v152, v153, v154, s[6:7]
	v_mul_f32_e32 v153, 0x37800000, v152
	v_cndmask_b32_e32 v152, v152, v153, vcc
	v_cmp_class_f32_e32 vcc, v34, v173
	s_nop 1
	v_cndmask_b32_e32 v34, v152, v34, vcc
	v_div_scale_f32 v152, s[6:7], v34, v34, 1.0
	v_rcp_f32_e32 v153, v152
	s_nop 0
	v_fma_f32 v154, -v152, v153, 1.0
	v_fmac_f32_e32 v153, v154, v153
	v_div_scale_f32 v154, vcc, 1.0, v34, 1.0
	v_mul_f32_e32 v155, v154, v153
	v_fma_f32 v156, -v152, v155, v154
	v_fmac_f32_e32 v155, v156, v153
	v_fma_f32 v152, -v152, v155, v154
	v_div_fmas_f32 v152, v152, v153, v155
	v_div_fixup_f32 v201, v152, v34, 1.0
	v_add_u32_e32 v152, 0xa0, v140
	v_ashrrev_i32_e32 v153, 31, v152
	v_lshlrev_b64 v[154:155], 6, v[152:153]
	v_lshl_add_u64 v[154:155], s[26:27], 0, v[154:155]
	v_mul_f32_e32 v164, 0x3f553b94, v201
	s_waitcnt vmcnt(2)
	v_pk_add_f32 v[162:163], v[218:219], v[222:223]
	v_pk_add_f32 v[166:167], v[216:217], v[220:221]
	s_waitcnt vmcnt(0)
	v_pk_add_f32 v[154:155], v[226:227], v[230:231]
	v_pk_add_f32 v[158:159], v[224:225], v[228:229]
	global_load_dwordx4 v[216:219], v[234:235], off offset:3104
	global_load_dwordx4 v[220:223], v[234:235], off offset:3120
	global_load_dwordx4 v[224:227], v[234:235], off offset:3072
	global_load_dwordx4 v[228:231], v[234:235], off offset:3088
	v_pk_add_f32 v[154:155], v[154:155], v[162:163]
	v_pk_add_f32 v[158:159], v[158:159], v[166:167]
	v_add_f32_e32 v154, v154, v155
	v_add_f32_e32 v34, v158, v159
	v_add_f32_e32 v34, v34, v154
	v_fmamk_f32 v34, v34, 0x3b000000, v169
	v_cmp_gt_f32_e32 vcc, s95, v34
	v_mul_f32_e32 v154, 0x4f800000, v34
	s_nop 0
	v_cndmask_b32_e32 v34, v34, v154, vcc
	v_sqrt_f32_e32 v154, v34
	s_nop 0
	v_add_u32_e32 v155, -1, v154
	v_fma_f32 v156, -v155, v154, v34
	v_cmp_ge_f32_e64 s[6:7], 0, v156
	v_add_u32_e32 v156, 1, v154
	s_nop 0
	v_cndmask_b32_e64 v155, v154, v155, s[6:7]
	v_fma_f32 v154, -v156, v154, v34
	v_cmp_lt_f32_e64 s[6:7], 0, v154
	s_nop 1
	v_cndmask_b32_e64 v154, v155, v156, s[6:7]
	v_mul_f32_e32 v155, 0x37800000, v154
	v_cndmask_b32_e32 v154, v154, v155, vcc
	v_cmp_class_f32_e32 vcc, v34, v173
	s_nop 1
	v_cndmask_b32_e32 v34, v154, v34, vcc
	v_div_scale_f32 v154, s[6:7], v34, v34, 1.0
	v_rcp_f32_e32 v155, v154
	s_nop 0
	v_fma_f32 v156, -v154, v155, 1.0
	v_fmac_f32_e32 v155, v156, v155
	v_div_scale_f32 v156, vcc, 1.0, v34, 1.0
	v_mul_f32_e32 v158, v156, v155
	v_fma_f32 v159, -v154, v158, v156
	v_fmac_f32_e32 v158, v159, v155
	v_fma_f32 v154, -v154, v158, v156
	v_div_fmas_f32 v154, v154, v155, v158
	v_div_fixup_f32 v204, v154, v34, 1.0
	v_add_u32_e32 v154, 0xb0, v140
	v_ashrrev_i32_e32 v155, 31, v154
	v_lshlrev_b64 v[158:159], 6, v[154:155]
	v_lshl_add_u64 v[158:159], s[26:27], 0, v[158:159]
	s_waitcnt vmcnt(2)
	v_pk_add_f32 v[166:167], v[218:219], v[222:223]
	v_pk_add_f32 v[170:171], v[216:217], v[220:221]
	s_waitcnt vmcnt(0)
	v_pk_add_f32 v[158:159], v[226:227], v[230:231]
	v_pk_add_f32 v[162:163], v[224:225], v[228:229]
	v_pk_add_f32 v[158:159], v[158:159], v[166:167]
	v_pk_add_f32 v[162:163], v[162:163], v[170:171]
	v_add_f32_e32 v156, v158, v159
	v_add_f32_e32 v34, v162, v163
	v_add_f32_e32 v34, v34, v156
	v_fmamk_f32 v34, v34, 0x3b000000, v169
	v_cmp_gt_f32_e32 vcc, s95, v34
	v_mul_f32_e32 v156, 0x4f800000, v34
	v_lshlrev_b64 v[186:187], 7, v[140:141]
	v_cndmask_b32_e32 v34, v34, v156, vcc
	v_sqrt_f32_e32 v156, v34
	v_lshlrev_b64 v[170:171], 7, v[148:149]
	v_lshlrev_b64 v[166:167], 7, v[150:151]
	v_add_u32_e32 v158, -1, v156
	v_fma_f32 v159, -v158, v156, v34
	v_cmp_ge_f32_e64 s[6:7], 0, v159
	v_add_u32_e32 v159, 1, v156
	s_nop 0
	v_cndmask_b32_e64 v158, v156, v158, s[6:7]
	v_fma_f32 v156, -v159, v156, v34
	v_cmp_lt_f32_e64 s[6:7], 0, v156
	s_nop 1
	v_cndmask_b32_e64 v156, v158, v159, s[6:7]
	v_mul_f32_e32 v158, 0x37800000, v156
	v_cndmask_b32_e32 v156, v156, v158, vcc
	v_cmp_class_f32_e32 vcc, v34, v173
	s_nop 1
	v_cndmask_b32_e32 v34, v156, v34, vcc
	v_div_scale_f32 v156, s[6:7], v34, v34, 1.0
	v_rcp_f32_e32 v158, v156
	s_nop 0
	v_fma_f32 v159, -v156, v158, 1.0
	v_fmac_f32_e32 v158, v159, v158
	v_div_scale_f32 v159, vcc, 1.0, v34, 1.0
	v_mul_f32_e32 v160, v159, v158
	v_fma_f32 v162, -v156, v160, v159
	v_fmac_f32_e32 v160, v162, v158
	v_fma_f32 v156, -v156, v160, v159
	v_div_fmas_f32 v156, v156, v158, v160
	v_div_fixup_f32 v207, v156, v34, 1.0
	v_lshl_or_b32 v34, v199, 3, s2
	v_or_b32_e32 v208, s91, v34
	v_mul_hi_i32 v34, v208, s96
	v_lshrrev_b32_e32 v156, 31, v34
	v_lshrrev_b32_e32 v34, 5, v34
	v_add_u32_e32 v34, v34, v156
	v_mul_lo_u32 v192, v34, s28
	v_sub_u32_e32 v188, v208, v192
	v_cmp_lt_i32_e32 vcc, s29, v188
	v_ashrrev_i32_e32 v193, 31, v192
	v_mul_f32_e32 v160, 0x3f553b94, v204
	v_lshlrev_b64 v[162:163], 7, v[152:153]
	v_mul_f32_e32 v156, 0x3f553b94, v207
	v_lshlrev_b64 v[158:159], 7, v[154:155]
	s_and_saveexec_b64 s[6:7], vcc
	s_xor_b64 s[6:7], exec, s[6:7]
	s_cbranch_execz .LBB0_1598
	v_add_u32_e32 v34, 0xffffff80, v188
	v_lshrrev_b32_e32 v34, 1, v34
	v_lshlrev_b64 v[188:189], 2, v[34:35]
	v_lshl_add_u64 v[190:191], s[14:15], 0, v[188:189]
	v_lshl_add_u64 v[194:195], v[190:191], 0, v[186:187]
	global_load_dwordx4 v[210:213], v[194:195], off
	v_lshl_add_u64 v[194:195], s[12:13], 0, v[188:189]
	v_lshl_add_u64 v[188:189], v[194:195], 0, v[186:187]
	global_load_dwordx4 v[214:217], v[188:189], off
	v_pk_mul_f32 v[222:223], v[22:23], v[184:185] op_sel_hi:[1,0]
	v_pk_mul_f32 v[218:219], v[18:19], v[184:185] op_sel_hi:[1,0]
	v_mov_b32_e32 v141, v35
	v_mov_b32_e32 v143, v35
	v_pk_mul_f32 v[220:221], v[24:25], v[184:185] op_sel_hi:[1,0]
	v_lshl_add_u64 v[188:189], v[192:193], 1, s[22:23]
	v_pk_mul_f32 v[192:193], v[20:21], v[184:185] op_sel_hi:[1,0]
	v_mad_i64_i32 v[224:225], s[24:25], v140, s0, v[188:189]
	s_waitcnt vmcnt(1)
	v_pk_mul_f32 v[228:229], v[222:223], v[210:211]
	v_pk_mul_f32 v[210:211], v[218:219], v[210:211]
	v_pk_mul_f32 v[226:227], v[220:221], v[212:213]
	s_waitcnt vmcnt(0)
	v_pk_fma_f32 v[218:219], v[218:219], v[214:215], v[228:229] neg_lo:[0,0,1] neg_hi:[0,0,1]
	v_pk_fma_f32 v[210:211], v[222:223], v[214:215], v[210:211]
	v_cvt_pk_fp8_f32 v141, v218, v219
	v_cvt_pk_fp8_f32 v143, v210, v211
	v_pk_mul_f32 v[212:213], v[192:193], v[212:213]
	v_pk_fma_f32 v[192:193], v[192:193], v[216:217], v[226:227] neg_lo:[0,0,1] neg_hi:[0,0,1]
	v_pk_fma_f32 v[210:211], v[220:221], v[216:217], v[212:213]
	v_cvt_pk_fp8_f32 v141, v192, v193 op_sel:[0,0,1]
	v_cvt_pk_fp8_f32 v143, v210, v211 op_sel:[0,0,1]
	v_lshl_add_u64 v[192:193], v[224:225], 0, v[34:35]
	v_lshl_add_u64 v[210:211], v[190:191], 0, v[182:183]
	global_store_dword v[192:193], v141, off offset:256
	global_store_dword v[192:193], v143, off offset:288
	global_load_dwordx4 v[210:213], v[210:211], off
	v_lshl_add_u64 v[192:193], v[194:195], 0, v[182:183]
	global_load_dwordx4 v[214:217], v[192:193], off
	v_pk_mul_f32 v[222:223], v[30:31], v[180:181] op_sel_hi:[1,0]
	v_pk_mul_f32 v[218:219], v[26:27], v[180:181] op_sel_hi:[1,0]
	v_mov_b32_e32 v141, v35
	v_mov_b32_e32 v143, v35
	v_pk_mul_f32 v[220:221], v[32:33], v[180:181] op_sel_hi:[1,0]
	v_pk_mul_f32 v[192:193], v[28:29], v[180:181] op_sel_hi:[1,0]
	v_mad_i64_i32 v[224:225], s[24:25], v142, s0, v[188:189]
	s_waitcnt vmcnt(1)
	v_pk_mul_f32 v[228:229], v[222:223], v[210:211]
	v_pk_mul_f32 v[210:211], v[218:219], v[210:211]
	s_waitcnt vmcnt(0)
	v_pk_fma_f32 v[218:219], v[218:219], v[214:215], v[228:229] neg_lo:[0,0,1] neg_hi:[0,0,1]
	v_pk_fma_f32 v[210:211], v[222:223], v[214:215], v[210:211]
	v_cvt_pk_fp8_f32 v141, v218, v219
	v_cvt_pk_fp8_f32 v143, v210, v211
	v_pk_mul_f32 v[226:227], v[220:221], v[212:213]
	v_pk_mul_f32 v[212:213], v[192:193], v[212:213]
	v_pk_fma_f32 v[192:193], v[192:193], v[216:217], v[226:227] neg_lo:[0,0,1] neg_hi:[0,0,1]
	v_pk_fma_f32 v[210:211], v[220:221], v[216:217], v[212:213]
	v_cvt_pk_fp8_f32 v141, v192, v193 op_sel:[0,0,1]
	v_cvt_pk_fp8_f32 v143, v210, v211 op_sel:[0,0,1]
	v_lshl_add_u64 v[192:193], v[224:225], 0, v[34:35]
	v_lshl_add_u64 v[210:211], v[190:191], 0, v[178:179]
	global_store_dword v[192:193], v141, off offset:256
	global_store_dword v[192:193], v143, off offset:288
	global_load_dwordx4 v[210:213], v[210:211], off
	v_lshl_add_u64 v[192:193], v[194:195], 0, v[178:179]
	global_load_dwordx4 v[214:217], v[192:193], off
	v_pk_mul_f32 v[222:223], v[6:7], v[176:177] op_sel_hi:[1,0]
	v_pk_mul_f32 v[218:219], v[2:3], v[176:177] op_sel_hi:[1,0]
	v_mov_b32_e32 v141, v35
	v_mov_b32_e32 v143, v35
	v_pk_mul_f32 v[220:221], v[8:9], v[176:177] op_sel_hi:[1,0]
	v_pk_mul_f32 v[192:193], v[4:5], v[176:177] op_sel_hi:[1,0]
	v_mad_i64_i32 v[224:225], s[24:25], v144, s0, v[188:189]
	s_waitcnt vmcnt(1)
	v_pk_mul_f32 v[228:229], v[222:223], v[210:211]
	v_pk_mul_f32 v[210:211], v[218:219], v[210:211]
	s_waitcnt vmcnt(0)
	v_pk_fma_f32 v[218:219], v[218:219], v[214:215], v[228:229] neg_lo:[0,0,1] neg_hi:[0,0,1]
	v_pk_fma_f32 v[210:211], v[222:223], v[214:215], v[210:211]
	v_cvt_pk_fp8_f32 v141, v218, v219
	v_cvt_pk_fp8_f32 v143, v210, v211
	v_pk_mul_f32 v[226:227], v[220:221], v[212:213]
	v_pk_mul_f32 v[212:213], v[192:193], v[212:213]
	v_pk_fma_f32 v[192:193], v[192:193], v[216:217], v[226:227] neg_lo:[0,0,1] neg_hi:[0,0,1]
	v_pk_fma_f32 v[210:211], v[220:221], v[216:217], v[212:213]
	v_cvt_pk_fp8_f32 v141, v192, v193 op_sel:[0,0,1]
	v_cvt_pk_fp8_f32 v143, v210, v211 op_sel:[0,0,1]
	v_lshl_add_u64 v[192:193], v[224:225], 0, v[34:35]
	v_lshl_add_u64 v[210:211], v[190:191], 0, v[174:175]
	global_store_dword v[192:193], v141, off offset:256
	global_store_dword v[192:193], v143, off offset:288
	global_load_dwordx4 v[210:213], v[210:211], off
	v_lshl_add_u64 v[192:193], v[194:195], 0, v[174:175]
	global_load_dwordx4 v[214:217], v[192:193], off
	v_pk_mul_f32 v[222:223], v[14:15], v[172:173] op_sel_hi:[1,0]
	v_pk_mul_f32 v[218:219], v[10:11], v[172:173] op_sel_hi:[1,0]
	v_mov_b32_e32 v141, v35
	v_mov_b32_e32 v143, v35
	v_pk_mul_f32 v[220:221], v[16:17], v[172:173] op_sel_hi:[1,0]
	v_pk_mul_f32 v[192:193], v[12:13], v[172:173] op_sel_hi:[1,0]
	v_mad_i64_i32 v[224:225], s[24:25], v146, s0, v[188:189]
	s_waitcnt vmcnt(1)
	v_pk_mul_f32 v[228:229], v[222:223], v[210:211]
	v_pk_mul_f32 v[210:211], v[218:219], v[210:211]
	s_waitcnt vmcnt(0)
	v_pk_fma_f32 v[218:219], v[218:219], v[214:215], v[228:229] neg_lo:[0,0,1] neg_hi:[0,0,1]
	v_pk_fma_f32 v[210:211], v[222:223], v[214:215], v[210:211]
	v_cvt_pk_fp8_f32 v141, v218, v219
	v_cvt_pk_fp8_f32 v143, v210, v211
	v_pk_mul_f32 v[226:227], v[220:221], v[212:213]
	v_pk_mul_f32 v[212:213], v[192:193], v[212:213]
	v_pk_fma_f32 v[192:193], v[192:193], v[216:217], v[226:227] neg_lo:[0,0,1] neg_hi:[0,0,1]
	v_pk_fma_f32 v[210:211], v[220:221], v[216:217], v[212:213]
	v_cvt_pk_fp8_f32 v141, v192, v193 op_sel:[0,0,1]
	v_cvt_pk_fp8_f32 v143, v210, v211 op_sel:[0,0,1]
	v_lshl_add_u64 v[192:193], v[224:225], 0, v[34:35]
	v_lshl_add_u64 v[210:211], v[190:191], 0, v[170:171]
	global_store_dword v[192:193], v141, off offset:256
	global_store_dword v[192:193], v143, off offset:288
	global_load_dwordx4 v[210:213], v[210:211], off
	v_lshl_add_u64 v[192:193], v[194:195], 0, v[170:171]
	global_load_dwordx4 v[214:217], v[192:193], off
	v_pk_mul_f32 v[222:223], v[120:121], v[168:169] op_sel_hi:[1,0]
	v_pk_mul_f32 v[218:219], v[116:117], v[168:169] op_sel_hi:[1,0]
	v_mov_b32_e32 v141, v35
	v_mov_b32_e32 v143, v35
	v_pk_mul_f32 v[220:221], v[122:123], v[168:169] op_sel_hi:[1,0]
	v_pk_mul_f32 v[192:193], v[118:119], v[168:169] op_sel_hi:[1,0]
	v_mad_i64_i32 v[224:225], s[24:25], v148, s0, v[188:189]
	s_waitcnt vmcnt(1)
	v_pk_mul_f32 v[228:229], v[222:223], v[210:211]
	v_pk_mul_f32 v[210:211], v[218:219], v[210:211]
	s_waitcnt vmcnt(0)
	v_pk_fma_f32 v[218:219], v[218:219], v[214:215], v[228:229] neg_lo:[0,0,1] neg_hi:[0,0,1]
	v_pk_fma_f32 v[210:211], v[222:223], v[214:215], v[210:211]
	v_cvt_pk_fp8_f32 v141, v218, v219
	v_cvt_pk_fp8_f32 v143, v210, v211
	v_pk_mul_f32 v[226:227], v[220:221], v[212:213]
	v_pk_mul_f32 v[212:213], v[192:193], v[212:213]
	v_pk_fma_f32 v[192:193], v[192:193], v[216:217], v[226:227] neg_lo:[0,0,1] neg_hi:[0,0,1]
	v_pk_fma_f32 v[210:211], v[220:221], v[216:217], v[212:213]
	v_cvt_pk_fp8_f32 v141, v192, v193 op_sel:[0,0,1]
	v_cvt_pk_fp8_f32 v143, v210, v211 op_sel:[0,0,1]
	v_lshl_add_u64 v[192:193], v[224:225], 0, v[34:35]
	v_lshl_add_u64 v[210:211], v[190:191], 0, v[166:167]
	global_store_dword v[192:193], v141, off offset:256
	global_store_dword v[192:193], v143, off offset:288
	global_load_dwordx4 v[210:213], v[210:211], off
	v_lshl_add_u64 v[192:193], v[194:195], 0, v[166:167]
	global_load_dwordx4 v[214:217], v[192:193], off
	v_pk_mul_f32 v[222:223], v[128:129], v[164:165] op_sel_hi:[1,0]
	v_pk_mul_f32 v[218:219], v[124:125], v[164:165] op_sel_hi:[1,0]
	v_mov_b32_e32 v141, v35
	v_mov_b32_e32 v143, v35
	v_pk_mul_f32 v[220:221], v[130:131], v[164:165] op_sel_hi:[1,0]
	v_pk_mul_f32 v[192:193], v[126:127], v[164:165] op_sel_hi:[1,0]
	v_mad_i64_i32 v[224:225], s[24:25], v150, s0, v[188:189]
	s_waitcnt vmcnt(1)
	v_pk_mul_f32 v[228:229], v[222:223], v[210:211]
	v_pk_mul_f32 v[210:211], v[218:219], v[210:211]
	s_waitcnt vmcnt(0)
	v_pk_fma_f32 v[218:219], v[218:219], v[214:215], v[228:229] neg_lo:[0,0,1] neg_hi:[0,0,1]
	v_pk_fma_f32 v[210:211], v[222:223], v[214:215], v[210:211]
	v_cvt_pk_fp8_f32 v141, v218, v219
	v_cvt_pk_fp8_f32 v143, v210, v211
	v_pk_mul_f32 v[226:227], v[220:221], v[212:213]
	v_pk_mul_f32 v[212:213], v[192:193], v[212:213]
	v_pk_fma_f32 v[192:193], v[192:193], v[216:217], v[226:227] neg_lo:[0,0,1] neg_hi:[0,0,1]
	v_pk_fma_f32 v[210:211], v[220:221], v[216:217], v[212:213]
	v_cvt_pk_fp8_f32 v141, v192, v193 op_sel:[0,0,1]
	v_cvt_pk_fp8_f32 v143, v210, v211 op_sel:[0,0,1]
	v_lshl_add_u64 v[192:193], v[224:225], 0, v[34:35]
	v_lshl_add_u64 v[210:211], v[190:191], 0, v[162:163]
	global_store_dword v[192:193], v141, off offset:256
	global_store_dword v[192:193], v143, off offset:288
	global_load_dwordx4 v[210:213], v[210:211], off
	v_lshl_add_u64 v[192:193], v[194:195], 0, v[162:163]
	global_load_dwordx4 v[214:217], v[192:193], off
	v_pk_mul_f32 v[222:223], v[104:105], v[160:161] op_sel_hi:[1,0]
	v_pk_mul_f32 v[218:219], v[100:101], v[160:161] op_sel_hi:[1,0]
	v_mov_b32_e32 v141, v35
	v_mov_b32_e32 v143, v35
	v_pk_mul_f32 v[220:221], v[106:107], v[160:161] op_sel_hi:[1,0]
	v_pk_mul_f32 v[192:193], v[102:103], v[160:161] op_sel_hi:[1,0]
	v_mad_i64_i32 v[224:225], s[24:25], v152, s0, v[188:189]
	v_lshl_add_u64 v[190:191], v[190:191], 0, v[158:159]
	v_lshl_add_u64 v[194:195], v[194:195], 0, v[158:159]
	v_mad_i64_i32 v[188:189], s[24:25], v154, s0, v[188:189]
	v_lshl_add_u64 v[188:189], v[188:189], 0, v[34:35]
	s_waitcnt vmcnt(1)
	v_pk_mul_f32 v[228:229], v[222:223], v[210:211]
	v_pk_mul_f32 v[210:211], v[218:219], v[210:211]
	s_waitcnt vmcnt(0)
	v_pk_fma_f32 v[218:219], v[218:219], v[214:215], v[228:229] neg_lo:[0,0,1] neg_hi:[0,0,1]
	v_pk_fma_f32 v[210:211], v[222:223], v[214:215], v[210:211]
	v_cvt_pk_fp8_f32 v141, v218, v219
	v_cvt_pk_fp8_f32 v143, v210, v211
	v_pk_mul_f32 v[226:227], v[220:221], v[212:213]
	v_pk_mul_f32 v[212:213], v[192:193], v[212:213]
	v_pk_fma_f32 v[192:193], v[192:193], v[216:217], v[226:227] neg_lo:[0,0,1] neg_hi:[0,0,1]
	v_pk_fma_f32 v[210:211], v[220:221], v[216:217], v[212:213]
	v_cvt_pk_fp8_f32 v141, v192, v193 op_sel:[0,0,1]
	v_cvt_pk_fp8_f32 v143, v210, v211 op_sel:[0,0,1]
	v_lshl_add_u64 v[192:193], v[224:225], 0, v[34:35]
	global_store_dword v[192:193], v141, off offset:256
	global_store_dword v[192:193], v143, off offset:288
	global_load_dwordx4 v[190:193], v[190:191], off
	v_pk_mul_f32 v[218:219], v[112:113], v[156:157] op_sel_hi:[1,0]
	global_load_dwordx4 v[210:213], v[194:195], off
	v_pk_mul_f32 v[214:215], v[108:109], v[156:157] op_sel_hi:[1,0]
	v_mov_b32_e32 v141, v35
	v_mov_b32_e32 v143, v35
	v_pk_mul_f32 v[216:217], v[114:115], v[156:157] op_sel_hi:[1,0]
	v_pk_mul_f32 v[194:195], v[110:111], v[156:157] op_sel_hi:[1,0]
	s_waitcnt vmcnt(1)
	v_pk_mul_f32 v[222:223], v[218:219], v[190:191]
	v_pk_mul_f32 v[190:191], v[214:215], v[190:191]
	s_waitcnt vmcnt(0)
	v_pk_fma_f32 v[214:215], v[214:215], v[210:211], v[222:223] neg_lo:[0,0,1] neg_hi:[0,0,1]
	v_pk_fma_f32 v[190:191], v[218:219], v[210:211], v[190:191]
	v_cvt_pk_fp8_f32 v141, v214, v215
	v_cvt_pk_fp8_f32 v143, v190, v191
	v_pk_mul_f32 v[220:221], v[216:217], v[192:193]
	v_pk_mul_f32 v[192:193], v[194:195], v[192:193]
	v_pk_fma_f32 v[190:191], v[194:195], v[212:213], v[220:221] neg_lo:[0,0,1] neg_hi:[0,0,1]
	v_pk_fma_f32 v[192:193], v[216:217], v[212:213], v[192:193]
	v_cvt_pk_fp8_f32 v141, v190, v191 op_sel:[0,0,1]
	v_cvt_pk_fp8_f32 v143, v192, v193 op_sel:[0,0,1]
	global_store_dword v[188:189], v141, off offset:256
	global_store_dword v[188:189], v143, off offset:288
